# v30 + SSD chunk loop: Y_off and state-update LDS reads batched with counted lgkmcnt, causal row blocks paired across SIMD partners
# speedup vs baseline: 1.0045x; 1.0045x over previous
; __device__ __forceinline__ void ssd_phase(const bf16_t* XBC, const float* DT  , const ss_t* SSq, const float* dtb, const bf16_t* Z, const float* a_log, const float* d_skip, bf16_t* YS, LAS unsigned char* lds, int tid, int wid, int lane, int bid, int G) {
;     const int fr = lane & 15, fq = lane >> 4;
;     LAS bf16_t* Ct = (LAS bf16_t*)(lds + SS_CT); LAS bf16_t* Bt = (LAS bf16_t*)(lds + SS_BT); LAS bf16_t* XT = (LAS bf16_t*)(lds + SS_XT); LAS bf16_t* XW = (LAS bf16_t*)(lds + SS_XW);
;     LAS bf16_t* Sin = (LAS bf16_t*)(lds + SS_SIN); LAS float* csbuf = (LAS float*)(lds + SS_CS);
;     for (int w = bid; w < 256; w += G) {
;         const int b = w >> 6, h = w & 63, g = h >> 3;
;         const float A = -expf(a_log[h]), Dh = d_skip[h], dtbh = dtb[h];
;         f32x4 Sacc[4];
; #pragma unroll
;         for (int pt = 0; pt < 4; ++pt) Sacc[pt] = (f32x4){0.f, 0.f, 0.f, 0.f};
;         u32x4 cr[4], br[4], xr2[2]; float d0 = 0.f, d1 = 0.f;
;         const unsigned voffC = (unsigned)(((tid >> 4) * SSD_CONV + 5120 + g * 128 + (tid & 15) * 8) * 2), voffX = (unsigned)(((tid & 127) * SSD_CONV + h * 64 + (tid >> 7) * 8) * 2);
;     ...
;         SSD_GLOADS(0);
;         if (wid == 0) { SSD_DTLOAD(0); SSD_SCAN(csbuf); SSD_DTLOAD(1); }
;         for (int c = 0; c < 16; ++c) {
;             const size_t row0 = (size_t)b * SEQ + (size_t)c * 128;
;             __syncthreads();
;             LAS float* csv = csbuf + (c & 1) * 256; LAS float* dtv = csv + 128;
; #pragma unroll
;             for (int pt = 0; pt < 4; ++pt) { u32x2 wv; wv.x = cvt_pk_bf16(Sacc[pt][0], Sacc[pt][1]); wv.y = cvt_pk_bf16(Sacc[pt][2], Sacc[pt][3]);
;                 *(LAS u32x2*)(Sin + (16 * pt + fr) * SS_RS + 16 * wid + 4 * fq) = wv; }
; #pragma unroll
;             for (int k = 0; k < 4; ++k) { const int it = tid + 512 * k, r = it >> 4, c16 = it & 15;
;                 *(LAS u32x4*)(Ct + r * SS_RS + c16 * 8) = cr[k]; *(LAS u32x4*)(Bt + r * SS_RS + c16 * 8) = br[k]; }
;             const float total = csv[127];
; #pragma unroll
;             for (int k = 0; k < 2; ++k) { const int it = tid + 512 * k, sx = it & 127, oct = it >> 7; const float dts = dtv[sx], dtw = dts * __expf(total - csv[sx]);
;                 const unsigned xw[4] = {xr2[k].x, xr2[k].y, xr2[k].z, xr2[k].w};
; #pragma unroll
;                 for (int j = 0; j < 4; ++j) { const float x0 = bflo(xw[j]), x1 = bfhi(xw[j]);
.LBB0_90:
	s_andn2_b64 vcc, exec, s[2:3]
	s_cbranch_vccnz .LBB0_147
	s_cmpk_gt_i32 s94, 0xff
	s_cbranch_scc1 .LBB0_147
	s_sub_i32 s30, 11, s95
	s_cmp_gt_i32 s95, 3
	s_cselect_b32 s95, s30, s95
	s_load_dwordx2 s[6:7], s[92:93], 0xe8
	v_writelane_b32 v255, s76, 6
	v_writelane_b32 v255, s72, 7
	v_ashrrev_i32_e32 v5, 4, v212
	s_waitcnt lgkmcnt(0)
	v_lshlrev_b32_e32 v3, 3, v212
	v_writelane_b32 v255, s73, 8
	v_writelane_b32 v255, s74, 9
	v_mul_lo_u32 v2, v5, s83
	v_and_b32_e32 v6, 0x78, v3
	v_writelane_b32 v255, s75, 10
	s_add_u32 s2, s6, 0x1ac00000
	v_or_b32_e32 v7, v2, v6
	v_lshlrev_b32_e32 v2, 4, v211
	v_mov_b32_e32 v3, v0
	v_writelane_b32 v255, s2, 11
	s_addc_u32 s2, s7, 0
	v_lshrrev_b32_e32 v4, 4, v211
	v_lshl_add_u64 v[2:3], s[6:7], 0, v[2:3]
	s_mov_b64 s[6:7], 0x20e30000
	v_add_u32_e32 v15, 0x400, v212
	v_lshl_add_u64 v[108:109], v[2:3], 0, s[6:7]
	v_lshlrev_b32_e32 v3, 3, v4
	v_lshl_add_u32 v2, v6, 1, 0
	s_movk_i32 s28, 0x110
	v_lshrrev_b32_e32 v15, 4, v15
	v_and_b32_e32 v8, -8, v5
	v_mad_u64_u32 v[112:113], s[18:19], v5, s28, v[2:3]
	v_add_u32_e32 v5, 0x200, v212
	v_mad_u64_u32 v[116:117], s[18:19], v15, s28, v[2:3]
	v_add_u32_e32 v15, 0x600, v212
	v_ashrrev_i32_e32 v5, 4, v5
	v_lshrrev_b32_e32 v15, 4, v15
	v_mad_u64_u32 v[114:115], s[18:19], v5, s28, v[2:3]
	v_mad_u64_u32 v[118:119], s[18:19], v15, s28, v[2:3]
	s_movk_i32 s18, 0x88
	v_and_b32_e32 v107, 0x7f, v212
	v_mul_lo_u32 v2, v8, s18
	v_mad_u32_u24 v121, v107, s83, v8
	v_add_u32_e32 v6, 0x88, v107
	v_readlane_b32 s20, v254, 4
	v_add_lshl_u32 v8, v2, v107, 1
	v_readlane_b32 s29, v254, 5
	v_add_lshl_u32 v15, v2, v6, 1
	v_add_u32_e32 v117, s20, v8
	v_add_u32_e32 v113, s29, v8
	v_add_u32_e32 v8, 0x110, v2
	v_add_u32_e32 v115, s29, v15
	v_add_u32_e32 v119, s20, v15
	v_add_lshl_u32 v15, v8, v107, 1
	v_add_lshl_u32 v8, v8, v6, 1
	v_add_u32_e32 v171, s29, v8
	v_add_u32_e32 v173, s20, v8
	v_add_u32_e32 v8, 0x220, v2
	v_add_u32_e32 v170, s29, v15
	v_add_u32_e32 v172, s20, v15
	v_add_lshl_u32 v15, v8, v107, 1
	v_add_lshl_u32 v8, v8, v6, 1
	v_add_u32_e32 v2, 0x330, v2
	v_add_u32_e32 v175, s29, v8
	v_add_u32_e32 v177, s20, v8
	v_add_lshl_u32 v8, v2, v107, 1
	v_add_lshl_u32 v2, v2, v6, 1
	v_add_u32_e32 v179, s29, v2
	v_add_u32_e32 v181, s20, v2
	v_and_b32_e32 v2, 0x1ffffff8, v5
	s_cmp_gt_u32 s38, 63
	v_mul_lo_u32 v2, v2, s18
	v_writelane_b32 v255, s2, 12
	s_cselect_b64 s[2:3], -1, 0
	s_cmp_lt_u32 s38, 64
	v_add_lshl_u32 v5, v2, v107, 1
	v_and_b32_e32 v1, 15, v212
	s_cselect_b64 s[8:9], -1, 0
	v_add_u32_e32 v178, s29, v8
	v_add_u32_e32 v180, s20, v8
	v_add_u32_e32 v182, s29, v5
	v_add_lshl_u32 v8, v2, v6, 1
	v_add_u32_e32 v184, s20, v5
	v_add_u32_e32 v5, 0x110, v2
	v_writelane_b32 v255, s8, 13
	v_lshl_or_b32 v110, s95, 4, v1
	v_lshlrev_b32_e32 v165, 2, v4
	v_add_u32_e32 v183, s29, v8
	v_add_u32_e32 v185, s20, v8
	v_add_lshl_u32 v8, v5, v107, 1
	v_add_lshl_u32 v5, v5, v6, 1
	v_writelane_b32 v255, s9, 14
	v_add_u32_e32 v187, s29, v5
	v_add_u32_e32 v189, s20, v5
	v_add_u32_e32 v5, 0x220, v2
	v_cmp_gt_i32_e64 s[18:19], v165, v110
	v_add_u32_e32 v186, s29, v8
	v_add_u32_e32 v188, s20, v8
	v_add_lshl_u32 v8, v5, v107, 1
	v_add_lshl_u32 v5, v5, v6, 1
	v_add_u32_e32 v2, 0x330, v2
	v_writelane_b32 v255, s18, 15
	v_add_u32_e32 v191, s29, v5
	v_add_u32_e32 v193, s20, v5
	v_add_lshl_u32 v5, v2, v107, 1
	v_add_lshl_u32 v2, v2, v6, 1
	v_writelane_b32 v255, s19, 16
	v_cmp_lt_i32_e64 s[18:19], v165, v110
	v_add_u32_e32 v195, s29, v2
	v_add_u32_e32 v214, s20, v2
	v_writelane_b32 v255, s18, 17
	v_or_b32_e32 v2, 2, v165
	v_and_b32_e32 v10, 48, v212
	v_writelane_b32 v255, s19, 18
	v_cmp_gt_i32_e64 s[18:19], v2, v110
	v_or_b32_e32 v2, 3, v165
	v_add_u32_e32 v167, s20, v10
	v_writelane_b32 v255, s18, 19
	v_add_u32_e32 v176, s20, v15
	v_add_u32_e32 v192, s20, v8
	v_writelane_b32 v255, s19, 20
	v_cmp_gt_i32_e64 s[18:19], v2, v110
	v_or_b32_e32 v2, 16, v165
	v_add_u32_e32 v213, s20, v5
	v_writelane_b32 v255, s18, 21
	s_mov_b32 s36, s95
	v_readlane_b32 s6, v254, 2
	v_writelane_b32 v255, s19, 22
	v_cmp_gt_i32_e64 s[18:19], v2, v110
	v_or_b32_e32 v2, 17, v165
	s_mov_b32 s31, s94
	v_writelane_b32 v255, s18, 23
	v_lshl_add_u32 v153, v211, 3, s6
	s_lshl_b32 s6, s95, 5
	v_writelane_b32 v255, s19, 24
	v_cmp_gt_i32_e64 s[18:19], v2, v110
	v_or_b32_e32 v2, 18, v165
	v_readlane_b32 s8, v254, 3
	v_writelane_b32 v255, s18, 25
	s_add_i32 s7, s8, s6
	s_add_i32 s6, s6, 0
	v_writelane_b32 v255, s19, 26
	v_cmp_gt_i32_e64 s[18:19], v2, v110
	v_or_b32_e32 v2, 19, v165
	s_mov_b64 s[34:35], s[92:93]
	v_writelane_b32 v255, s18, 27
	s_cmp_gt_i32 s95, -1
	v_mov_b32_e32 v12, 0x1100
	v_writelane_b32 v255, s19, 28
	v_cmp_gt_i32_e64 s[18:19], v2, v110
	v_or_b32_e32 v2, 32, v165
	v_cmp_gt_i32_e64 s[20:21], v2, v110
	v_writelane_b32 v255, s18, 29
	v_or_b32_e32 v2, 33, v165
	v_mov_b32_e32 v13, 0x2200
	v_writelane_b32 v255, s19, 30
	v_writelane_b32 v255, s20, 31
	s_cselect_b64 s[94:95], -1, 0
	s_cmp_gt_i32 s36, 0
	v_writelane_b32 v255, s21, 32
	v_cmp_gt_i32_e64 s[20:21], v2, v110
	v_or_b32_e32 v2, 34, v165
	v_cmp_gt_i32_e64 s[40:41], v2, v110
	v_or_b32_e32 v2, 35, v165
	v_cmp_gt_i32_e64 s[42:43], v2, v110
	v_or_b32_e32 v2, 48, v165
	v_cmp_gt_i32_e64 s[44:45], v2, v110
	v_or_b32_e32 v2, 49, v165
	v_cmp_gt_i32_e64 s[46:47], v2, v110
	v_or_b32_e32 v2, 50, v165
	v_writelane_b32 v255, s20, 33
	v_cmp_gt_i32_e64 s[48:49], v2, v110
	v_or_b32_e32 v2, 51, v165
	v_writelane_b32 v255, s21, 34
	v_cmp_gt_i32_e64 s[50:51], v2, v110
	v_or_b32_e32 v2, 64, v165
	v_cmp_gt_i32_e64 s[52:53], v2, v110
	v_or_b32_e32 v2, 0x41, v165
	v_writelane_b32 v255, s36, 35
	v_cmp_gt_i32_e64 s[54:55], v2, v110
	v_or_b32_e32 v2, 0x42, v165
	v_writelane_b32 v255, s31, 36
	v_cmp_gt_i32_e64 s[56:57], v2, v110
	v_or_b32_e32 v2, 0x43, v165
	v_writelane_b32 v255, s31, 37
	v_cmp_gt_i32_e64 s[58:59], v2, v110
	v_or_b32_e32 v2, 0x50, v165
	v_writelane_b32 v255, s34, 38
	s_load_dwordx4 s[84:87], s[34:35], 0x90
	v_cmp_gt_i32_e64 s[60:61], v2, v110
	v_or_b32_e32 v2, 0x70, v211
	v_mad_u32_u24 v12, v1, s28, v12
	v_mad_u32_u24 v13, v1, s28, v13
	v_or_b32_e32 v14, 48, v211
	v_add_u32_e32 v174, s29, v15
	v_add_u32_e32 v190, s29, v8
	v_add_u32_e32 v194, s29, v5
	s_cselect_b64 s[92:93], -1, 0
	s_cmp_gt_i32 s36, 1
	v_mul_u32_u24_e32 v19, 0x110, v2
	v_add_u32_e32 v2, s29, v3
	v_readlane_b32 s29, v254, 6
	s_cselect_b64 s[18:19], -1, 0
	s_cmp_gt_i32 s36, 2
	v_mad_u32_u24 v215, v1, s28, v2
	v_add_u32_e32 v216, v2, v12
	v_add_u32_e32 v217, v2, v13
	v_mad_u32_u24 v218, v14, s28, v2
	v_add_u32_e32 v2, s29, v3
	v_readlane_b32 s29, v254, 7
	s_cselect_b64 s[20:21], -1, 0
	s_cmp_gt_i32 s36, 3
	v_mad_u32_u24 v219, v1, s28, v2
	v_add_u32_e32 v220, v2, v12
	v_add_u32_e32 v221, v2, v13
	v_mad_u32_u24 v222, v14, s28, v2
	v_add_u32_e32 v2, s29, v3
	v_readlane_b32 s29, v254, 8
	v_writelane_b32 v255, s35, 39
	s_cselect_b64 s[22:23], -1, 0
	s_cmp_gt_i32 s36, 4
	v_mad_u32_u24 v223, v1, s28, v2
	v_add_u32_e32 v224, v2, v12
	v_add_u32_e32 v225, v2, v13
	v_mad_u32_u24 v226, v14, s28, v2
	v_add_u32_e32 v2, s29, v3
	s_waitcnt lgkmcnt(0)
; #define LAS __attribute__((address_space(3)))
; __device__ __forceinline__ void ssd_phase(const bf16_t* XBC, const float* DT  , const ss_t* SSq, const float* dtb, const bf16_t* Z, const float* a_log, const float* d_skip, bf16_t* YS, LAS unsigned char* lds, int tid, int wid, int lane, int bid, int G) {
;     ...
;             const int lrow = 16 * wid + fr; const float csl = csv[lrow];
;             bf16x8 Cfr[4];
; #pragma unroll
;             for (int ks = 0; ks < 4; ++ks) Cfr[ks] = *(const LAS bf16x8*)(Ct + lrow * SS_RS + 32 * ks + 8 * fq);
;             unsigned gp[8][2];
; #pragma unroll
;             for (int t = 0; t < 8; ++t) {
;                 if (t <= wid) {
;                     f32x4 acc = (f32x4){0.f, 0.f, 0.f, 0.f};
; #pragma unroll
;                     for (int ks = 0; ks < 4; ++ks) { const bf16x8 bfr = *(const LAS bf16x8*)(Bt + (16 * t + fr) * SS_RS + 32 * ks + 8 * fq); acc = __builtin_amdgcn_mfma_f32_16x16x32_bf16(bfr, Cfr[ks], acc, 0, 0, 0); }
;                     const f32x4 cs4 = *(const LAS f32x4*)(csv + 16 * t + 4 * fq); float v[4];
; #pragma unroll
;                     for (int r = 0; r < 4; ++r) { const int sx = 16 * t + 4 * fq + r; v[r] = (sx <= lrow) ? acc[r] * __expf(csl - cs4[r]) : 0.f; }
	v_writelane_b32 v255, s84, 40
	v_add_u32_e32 v157, s7, v3
	v_mul_lo_u32 v9, v110, s28
	s_movk_i32 s30, 0x3000
	s_cselect_b64 s[24:25], -1, 0
	s_cmp_gt_i32 s36, 5
	v_mad_u32_u24 v227, v1, s28, v2
	v_add_u32_e32 v228, v2, v12
	v_add_u32_e32 v229, v2, v13
	v_mad_u32_u24 v230, v14, s28, v2
	v_mov_b64_e32 v[2:3], 0x1ac00040
	v_writelane_b32 v255, s85, 41
	v_lshlrev_b32_e32 v106, 1, v211
	v_add_u32_e32 v9, 0, v9
	v_add_u32_e32 v164, 0, v10
	v_lshl_add_u32 v11, v1, 1, s6
	v_mul_u32_u24_e32 v168, 0x110, v1
	v_or_b32_e32 v5, 0x51, v165
	v_or_b32_e32 v6, 0x52, v165
	v_or_b32_e32 v8, 0x53, v165
	s_cselect_b64 s[26:27], -1, 0
	v_or_b32_e32 v15, 0x60, v165
	v_or_b32_e32 v16, 0x61, v165
	v_or_b32_e32 v17, 0x62, v165
	v_or_b32_e32 v18, 0x63, v165
	s_cmp_gt_i32 s36, 6
	v_or_b32_e32 v20, 0x70, v165
	v_or_b32_e32 v21, 0x71, v165
	v_or_b32_e32 v22, 0x72, v165
	v_or_b32_e32 v23, 0x73, v165
	v_mul_u32_u24_e32 v1, 0x880, v4
	v_ashrrev_i32_e32 v111, 31, v110
	v_mad_i64_i32 v[124:125], s[28:29], v110, s30, v[2:3]
	v_mov_b32_e32 v2, 0x20e30800
	v_writelane_b32 v255, s86, 42
	v_add_u32_e32 v166, s8, v10
	v_cmp_eq_u32_e64 s[6:7], 0, v211
	v_cmp_gt_u32_e64 s[8:9], 2, v211
	v_cmp_gt_u32_e64 s[10:11], 4, v211
	v_cmp_gt_u32_e64 s[12:13], 8, v211
	v_cmp_gt_u32_e64 s[14:15], 16, v211
	v_cmp_gt_u32_e64 s[16:17], 32, v211
	v_mul_u32_u24_e32 v169, 0x110, v14
	v_add_u32_e32 v231, 0x1400, v7
	v_or_b32_e32 v120, 0x80, v106
	v_lshlrev_b32_e32 v122, 9, v211
	v_mov_b32_e32 v123, v0
	v_lshl_or_b32 v126, v211, 4, v2
	v_mov_b32_e32 v127, v0
	v_lshlrev_b64 v[128:129], 13, v[110:111]
	v_add_u32_e32 v111, v9, v10
	v_add_u32_e32 v232, v164, v19
	v_add_u32_e32 v233, v11, v1
	s_mov_b32 s36, s31
	v_cmp_gt_i32_e64 s[62:63], v5, v110
	v_cmp_gt_i32_e64 s[64:65], v6, v110
	v_cmp_gt_i32_e64 s[66:67], v8, v110
	v_cmp_gt_i32_e64 s[68:69], v15, v110
	v_cmp_gt_i32_e64 s[70:71], v16, v110
	v_cmp_gt_i32_e64 s[72:73], v17, v110
	v_cmp_gt_i32_e64 s[74:75], v18, v110
	s_cselect_b64 s[28:29], -1, 0
	v_cmp_gt_i32_e64 s[76:77], v20, v110
	v_cmp_gt_i32_e64 s[78:79], v21, v110
	v_cmp_gt_i32_e64 s[80:81], v22, v110
	v_cmp_gt_i32_e64 s[82:83], v23, v110
	v_writelane_b32 v255, s87, 43
	s_branch .LBB0_94

; #define LAS __attribute__((address_space(3)))
; __device__ __forceinline__ unsigned cvt_pk_bf16(float lo, float hi) { unsigned r; asm volatile("v_cvt_pk_bf16_f32 %0, %1, %2" : "=v"(r) : "v"(lo), "v"(hi)); return r; }
; __device__ __forceinline__ float bflo(unsigned w) { return __uint_as_float(w << 16); }
; __device__ __forceinline__ float bfhi(unsigned w) { return __uint_as_float(w & 0xffff0000u); }
; __device__ __forceinline__ float fsilu(float x) { return x * fsigmoid(x); }
; __device__ __forceinline__ void ssd_phase(const bf16_t* XBC, const float* DT  , const ss_t* SSq, const float* dtb, const bf16_t* Z, const float* a_log, const float* d_skip, bf16_t* YS, LAS unsigned char* lds, int tid, int wid, int lane, int bid, int G) {
;     ...
; #pragma unroll
;             for (int ks = 0; ks < 4; ++ks) {
; #pragma unroll
;                 for (int pt = 0; pt < 4; ++pt) { const bf16x8 sfr = *(const LAS bf16x8*)(Sin + (16 * pt + fr) * SS_RS + 32 * ks + 8 * fq); acco[pt] = __builtin_amdgcn_mfma_f32_16x16x32_bf16(sfr, Cfr[ks], acco[pt], 0, 0, 0); }
;                 __builtin_amdgcn_sched_barrier(0); }
;             {
;                 const float el = __expf(csl); const size_t grow = row0 + lrow;
; #pragma unroll
;                 for (int pt = 0; pt < 4; ++pt) { const int pc = h * 64 + 16 * pt + 4 * fq;
;                     const u32x2 xv = *(const u32x2*)(XBC + grow * SSD_CONV + pc), zv = *(const u32x2*)(Z + grow * SSD_INNER + pc);
;                     const float xs[4] = {bflo(xv.x), bfhi(xv.x), bflo(xv.y), bfhi(xv.y)}, zs[4] = {bflo(zv.x), bfhi(zv.x), bflo(zv.y), bfhi(zv.y)}; float y[4];
; #pragma unroll
;                     for (int r = 0; r < 4; ++r) y[r] = (accd[pt][r] + el * acco[pt][r] + Dh * xs[r]) * fsilu(zs[r]);
;                     u32x2 o; o.x = cvt_pk_bf16(y[0], y[1]); o.y = cvt_pk_bf16(y[2], y[3]); *(u32x2*)(YS + grow * SSD_INNER + pc) = o; }
;             }
.LBB0_100:
	v_add_u32_e32 v1, v166, v168
	v_add_u32_e32 v2, v166, v169
	ds_read_b128 v[12:15], v1
	ds_read_b128 v[94:97], v1 offset:4352
	ds_read_b128 v[98:101], v1 offset:8704
	ds_read_b128 v[236:239], v2
	s_waitcnt lgkmcnt(3)
	v_mfma_f32_16x16x32_bf16 v[12:15], v[12:15], v[86:89], 0
	s_waitcnt lgkmcnt(2)
	v_mfma_f32_16x16x32_bf16 v[94:97], v[94:97], v[86:89], 0
	s_waitcnt lgkmcnt(1)
	v_mfma_f32_16x16x32_bf16 v[98:101], v[98:101], v[86:89], 0
	s_waitcnt lgkmcnt(0)
	v_mfma_f32_16x16x32_bf16 v[86:89], v[236:239], v[86:89], 0
	ds_read_b128 v[240:243], v1 offset:64
	ds_read_b128 v[244:247], v1 offset:4416
	ds_read_b128 v[248:251], v1 offset:8768
	ds_read_b128 v[148:151], v2 offset:64
	s_waitcnt lgkmcnt(3)
	v_mfma_f32_16x16x32_bf16 v[12:15], v[240:243], v[82:85], v[12:15]
	s_waitcnt lgkmcnt(2)
	v_mfma_f32_16x16x32_bf16 v[94:97], v[244:247], v[82:85], v[94:97]
	s_waitcnt lgkmcnt(1)
	v_mfma_f32_16x16x32_bf16 v[98:101], v[248:251], v[82:85], v[98:101]
	s_waitcnt lgkmcnt(0)
	v_mfma_f32_16x16x32_bf16 v[86:89], v[148:151], v[82:85], v[86:89]
	ds_read_b128 v[240:243], v1 offset:128
	ds_read_b128 v[244:247], v1 offset:4480
	ds_read_b128 v[248:251], v1 offset:8832
	ds_read_b128 v[148:151], v2 offset:128
	s_waitcnt lgkmcnt(3)
	v_mfma_f32_16x16x32_bf16 v[12:15], v[240:243], v[78:81], v[12:15]
	s_waitcnt lgkmcnt(2)
	v_mfma_f32_16x16x32_bf16 v[94:97], v[244:247], v[78:81], v[94:97]
	s_waitcnt lgkmcnt(1)
	v_mfma_f32_16x16x32_bf16 v[98:101], v[248:251], v[78:81], v[98:101]
	s_waitcnt lgkmcnt(0)
	v_mfma_f32_16x16x32_bf16 v[86:89], v[148:151], v[78:81], v[86:89]
	ds_read_b128 v[240:243], v1 offset:192
	ds_read_b128 v[244:247], v1 offset:4544
	ds_read_b128 v[248:251], v1 offset:8896
	ds_read_b128 v[148:151], v2 offset:192
	s_waitcnt lgkmcnt(3)
	v_mfma_f32_16x16x32_bf16 v[236:239], v[240:243], v[74:77], v[12:15]
	s_waitcnt lgkmcnt(2)
	v_mfma_f32_16x16x32_bf16 v[82:85], v[244:247], v[74:77], v[94:97]
	s_waitcnt lgkmcnt(1)
	v_mfma_f32_16x16x32_bf16 v[78:81], v[248:251], v[74:77], v[98:101]
	s_waitcnt lgkmcnt(0)
	v_mfma_f32_16x16x32_bf16 v[12:15], v[148:151], v[74:77], v[86:89]
	v_lshl_add_u64 v[76:77], s[38:39], 0, v[160:161]
	s_mov_b32 s30, 0x10c00000
	v_add_co_u32_e32 v2, vcc, s30, v76
	v_lshl_add_u64 v[16:17], s[38:39], 0, v[140:141]
	s_nop 0
	v_addc_co_u32_e32 v3, vcc, 0, v77, vcc
	global_load_dwordx2 v[74:75], v[16:17], off offset:-64
	global_load_dwordx2 v[86:87], v[2:3], off
	v_mul_f32_e32 v1, 0x3fb8aa3b, v131
	v_exp_f32_e32 v1, v1
	s_mov_b32 s30, 0x14c00000
	v_fma_f32 v94, v1, v236, v102
	v_fmac_f32_e32 v105, v1, v239
	v_fma_f32 v82, v1, v82, v90
	v_fmac_f32_e32 v93, v1, v85
	v_fma_f32 v8, v1, v78, v8
	v_fma_f32 v79, v1, v79, v9
	v_fma_f32 v10, v1, v80, v10
	v_fmac_f32_e32 v11, v1, v81
	v_fma_f32 v4, v1, v12, v4
	v_fmac_f32_e32 v7, v1, v15
	s_waitcnt vmcnt(1)
	v_lshlrev_b32_e32 v88, 16, v74
	s_waitcnt vmcnt(0)
	v_lshlrev_b32_e32 v89, 16, v86
	v_mul_f32_e32 v95, 0xbfb8aa3b, v89
	v_exp_f32_e32 v95, v95
	s_nop 0
	v_add_f32_e32 v95, 1.0, v95
	v_rcp_f32_e32 v131, v95
	v_fma_f32 v95, v1, v237, v103
	v_pk_mul_f32 v[88:89], v[130:131], v[88:89]
	s_nop 0
	v_add_f32_e32 v88, v94, v88
	v_mul_f32_e32 v94, v88, v89
	v_and_b32_e32 v89, 0xffff0000, v86
	v_and_b32_e32 v88, 0xffff0000, v74
	v_mul_f32_e32 v74, 0xbfb8aa3b, v89
	v_exp_f32_e32 v74, v74
	s_nop 0
	v_add_f32_e32 v74, 1.0, v74
	v_rcp_f32_e32 v131, v74
	s_nop 0
	v_pk_mul_f32 v[88:89], v[130:131], v[88:89]
	s_nop 0
	v_add_f32_e32 v74, v95, v88
	v_mul_f32_e32 v95, v74, v89
	v_lshlrev_b32_e32 v89, 16, v87
	v_mul_f32_e32 v86, 0xbfb8aa3b, v89
	v_exp_f32_e32 v86, v86
	v_lshlrev_b32_e32 v88, 16, v75
	v_fma_f32 v74, v1, v238, v104
	v_and_b32_e32 v87, 0xffff0000, v87
	v_add_f32_e32 v86, 1.0, v86
	v_rcp_f32_e32 v131, v86
	v_and_b32_e32 v86, 0xffff0000, v75
	v_pk_mul_f32 v[88:89], v[130:131], v[88:89]
	s_nop 0
	v_add_f32_e32 v74, v74, v88
	v_mul_f32_e32 v88, v74, v89
	v_mul_f32_e32 v74, 0xbfb8aa3b, v87
	v_exp_f32_e32 v74, v74
	s_nop 0
	v_add_f32_e32 v74, 1.0, v74
	v_rcp_f32_e32 v131, v74
	s_nop 0
	v_pk_mul_f32 v[74:75], v[130:131], v[86:87]
	s_nop 0
	v_add_f32_e32 v74, v105, v74
	v_mul_f32_e32 v74, v74, v75
	v_cvt_pk_bf16_f32 v86, v94, v95
	v_cvt_pk_bf16_f32 v87, v88, v74
	v_add_co_u32_e32 v74, vcc, s30, v76
	s_mov_b32 s30, 0x5040100
	s_nop 0
	v_addc_co_u32_e32 v75, vcc, 0, v77, vcc
	global_store_dwordx2 v[74:75], v[86:87], off
	global_load_dwordx2 v[76:77], v[16:17], off offset:-32
	s_nop 0
	global_load_dwordx2 v[86:87], v[2:3], off offset:32
	s_waitcnt vmcnt(1)
	v_lshlrev_b32_e32 v88, 16, v76
	s_waitcnt vmcnt(0)
	v_lshlrev_b32_e32 v89, 16, v86
	v_mul_f32_e32 v90, 0xbfb8aa3b, v89
	v_exp_f32_e32 v90, v90
	s_nop 0
	v_add_f32_e32 v90, 1.0, v90
	v_rcp_f32_e32 v131, v90
	s_nop 0
	v_pk_mul_f32 v[88:89], v[130:131], v[88:89]
	s_nop 0
	v_add_f32_e32 v82, v82, v88
	v_mul_f32_e32 v88, v82, v89
	v_fma_f32 v89, v1, v83, v91
	v_and_b32_e32 v83, 0xffff0000, v86
	v_and_b32_e32 v82, 0xffff0000, v76
	v_mul_f32_e32 v76, 0xbfb8aa3b, v83
	v_exp_f32_e32 v76, v76
	s_nop 0
	v_add_f32_e32 v76, 1.0, v76
	v_rcp_f32_e32 v131, v76
	s_nop 0
	v_pk_mul_f32 v[82:83], v[130:131], v[82:83]
	s_nop 0
	v_add_f32_e32 v76, v89, v82
	v_mul_f32_e32 v86, v76, v83
	v_lshlrev_b32_e32 v83, 16, v87
	v_fma_f32 v76, v1, v84, v92
	v_mul_f32_e32 v84, 0xbfb8aa3b, v83
	v_exp_f32_e32 v84, v84
	v_lshlrev_b32_e32 v82, 16, v77
	v_add_f32_e32 v84, 1.0, v84
	v_rcp_f32_e32 v131, v84
	s_nop 0
	v_pk_mul_f32 v[82:83], v[130:131], v[82:83]
	s_nop 0
	v_add_f32_e32 v76, v76, v82
	v_mul_f32_e32 v84, v76, v83
	v_and_b32_e32 v83, 0xffff0000, v87
	v_mul_f32_e32 v76, 0xbfb8aa3b, v83
	v_exp_f32_e32 v76, v76
	v_and_b32_e32 v82, 0xffff0000, v77
	v_add_f32_e32 v76, 1.0, v76
	v_rcp_f32_e32 v131, v76
	s_nop 0
	v_pk_mul_f32 v[76:77], v[130:131], v[82:83]
	s_nop 0
	v_add_f32_e32 v76, v93, v76
	v_mul_f32_e32 v77, v76, v77
	v_cvt_pk_bf16_f32 v76, v88, v86
	v_cvt_pk_bf16_f32 v77, v84, v77
	global_store_dwordx2 v[74:75], v[76:77], off offset:32
	global_load_dwordx2 v[76:77], v[16:17], off
	s_nop 0
	global_load_dwordx2 v[82:83], v[2:3], off offset:64
	s_waitcnt vmcnt(1)
; #define LAS __attribute__((address_space(3)))
; __device__ __forceinline__ unsigned cvt_pk_bf16(float lo, float hi) { unsigned r; asm volatile("v_cvt_pk_bf16_f32 %0, %1, %2" : "=v"(r) : "v"(lo), "v"(hi)); return r; }
; __device__ __forceinline__ float fsilu(float x) { return x * fsigmoid(x); }
; __device__ __forceinline__ void ssd_phase(const bf16_t* XBC, const float* DT  , const ss_t* SSq, const float* dtb, const bf16_t* Z, const float* a_log, const float* d_skip, bf16_t* YS, LAS unsigned char* lds, int tid, int wid, int lane, int bid, int G) {
;     ...
;                     for (int r = 0; r < 4; ++r) y[r] = (accd[pt][r] + el * acco[pt][r] + Dh * xs[r]) * fsilu(zs[r]);
;                     u32x2 o; o.x = cvt_pk_bf16(y[0], y[1]); o.y = cvt_pk_bf16(y[2], y[3]); *(u32x2*)(YS + grow * SSD_INNER + pc) = o; }
;             }
;             {
;                 const float eT = __expf(total);
; #pragma unroll
;                 for (int pt = 0; pt < 4; ++pt) Sacc[pt] = Sacc[pt] * eT;
; #pragma unroll
;                 for (int u = 0; u < 4; ++u) { unsigned short bs[8];
; #pragma unroll
;                     for (int e = 0; e < 8; ++e) bs[e] = Bt[(32 * u + 8 * fq + e) * SS_RS + 16 * wid + fr];
;                     u32x4 bq; bq.x = (unsigned)bs[0] | ((unsigned)bs[1] << 16); bq.y = (unsigned)bs[2] | ((unsigned)bs[3] << 16); bq.z = (unsigned)bs[4] | ((unsigned)bs[5] << 16); bq.w = (unsigned)bs[6] | ((unsigned)bs[7] << 16);
;                     const bf16x8 pfr = __builtin_bit_cast(bf16x8, bq);
; #pragma unroll
;                     for (int pt = 0; pt < 4; ++pt) { const bf16x8 qfr = *(const LAS bf16x8*)(XW + (16 * pt + fr) * SS_RS + 32 * u + 8 * fq); Sacc[pt] = __builtin_amdgcn_mfma_f32_16x16x32_bf16(pfr, qfr, Sacc[pt], 0, 0, 0); }
	v_lshlrev_b32_e32 v84, 16, v76
	s_waitcnt vmcnt(0)
	v_lshlrev_b32_e32 v85, 16, v82
	v_mul_f32_e32 v78, 0xbfb8aa3b, v85
	v_exp_f32_e32 v78, v78
	v_and_b32_e32 v9, 0xffff0000, v82
	v_add_f32_e32 v78, 1.0, v78
	v_rcp_f32_e32 v131, v78
	s_nop 0
	v_pk_mul_f32 v[84:85], v[130:131], v[84:85]
	s_nop 0
	v_add_f32_e32 v8, v8, v84
	v_mul_f32_e32 v78, v8, v85
	v_and_b32_e32 v8, 0xffff0000, v76
	v_mul_f32_e32 v76, 0xbfb8aa3b, v9
	v_exp_f32_e32 v76, v76
	s_nop 0
	v_add_f32_e32 v76, 1.0, v76
	v_rcp_f32_e32 v131, v76
	s_nop 0
	v_pk_mul_f32 v[8:9], v[130:131], v[8:9]
	s_nop 0
	v_add_f32_e32 v8, v79, v8
	v_mul_f32_e32 v76, v8, v9
	v_lshlrev_b32_e32 v9, 16, v83
	v_mul_f32_e32 v79, 0xbfb8aa3b, v9
	v_exp_f32_e32 v79, v79
	v_lshlrev_b32_e32 v8, 16, v77
	v_add_f32_e32 v79, 1.0, v79
	v_rcp_f32_e32 v131, v79
	s_nop 0
	v_pk_mul_f32 v[8:9], v[130:131], v[8:9]
	s_nop 0
	v_add_f32_e32 v8, v10, v8
	v_mul_f32_e32 v10, v8, v9
	v_and_b32_e32 v9, 0xffff0000, v83
	v_and_b32_e32 v8, 0xffff0000, v77
	v_mul_f32_e32 v77, 0xbfb8aa3b, v9
	v_exp_f32_e32 v77, v77
	s_nop 0
	v_add_f32_e32 v77, 1.0, v77
	v_rcp_f32_e32 v131, v77
	s_nop 0
	v_pk_mul_f32 v[8:9], v[130:131], v[8:9]
	s_nop 0
	v_add_f32_e32 v8, v11, v8
	v_mul_f32_e32 v9, v8, v9
	v_cvt_pk_bf16_f32 v8, v78, v76
	v_cvt_pk_bf16_f32 v9, v10, v9
	global_store_dwordx2 v[74:75], v[8:9], off offset:64
	global_load_dwordx2 v[8:9], v[16:17], off offset:32
	s_nop 0
	global_load_dwordx2 v[2:3], v[2:3], off offset:96
	s_waitcnt vmcnt(1)
	v_lshlrev_b32_e32 v10, 16, v8
	s_waitcnt vmcnt(0)
	v_lshlrev_b32_e32 v11, 16, v2
	v_mul_f32_e32 v12, 0xbfb8aa3b, v11
	v_exp_f32_e32 v12, v12
	s_nop 0
	v_add_f32_e32 v12, 1.0, v12
	v_rcp_f32_e32 v131, v12
	s_nop 0
	v_pk_mul_f32 v[10:11], v[130:131], v[10:11]
	s_nop 0
	v_add_f32_e32 v4, v4, v10
	v_mul_f32_e32 v10, v4, v11
	v_fma_f32 v11, v1, v13, v5
	v_and_b32_e32 v5, 0xffff0000, v2
	v_mul_f32_e32 v2, 0xbfb8aa3b, v5
	v_exp_f32_e32 v2, v2
	v_and_b32_e32 v4, 0xffff0000, v8
	v_add_f32_e32 v2, 1.0, v2
	v_rcp_f32_e32 v131, v2
	s_nop 0
	v_pk_mul_f32 v[4:5], v[130:131], v[4:5]
	s_nop 0
	v_add_f32_e32 v2, v11, v4
	v_mul_f32_e32 v8, v2, v5
	v_lshlrev_b32_e32 v5, 16, v3
	v_fma_f32 v2, v1, v14, v6
	v_mul_f32_e32 v6, 0xbfb8aa3b, v5
	v_exp_f32_e32 v6, v6
	v_and_b32_e32 v3, 0xffff0000, v3
	v_mul_f32_e32 v1, 0xbfb8aa3b, v3
	v_exp_f32_e32 v1, v1
	v_add_f32_e32 v6, 1.0, v6
	v_rcp_f32_e32 v131, v6
	v_lshlrev_b32_e32 v4, 16, v9
	v_add_f32_e32 v1, 1.0, v1
	v_pk_mul_f32 v[4:5], v[130:131], v[4:5]
	v_rcp_f32_e32 v131, v1
	v_add_f32_e32 v2, v2, v4
	v_mul_f32_e32 v4, v2, v5
	v_and_b32_e32 v2, 0xffff0000, v9
	v_pk_mul_f32 v[2:3], v[130:131], v[2:3]
	s_nop 0
	v_add_f32_e32 v1, v7, v2
	v_mul_f32_e32 v1, v1, v3
	v_cvt_pk_bf16_f32 v2, v10, v8
	v_cvt_pk_bf16_f32 v3, v4, v1
	v_mul_f32_e32 v1, 0x3fb8aa3b, v235
	global_store_dwordx2 v[74:75], v[2:3], off offset:96
	v_exp_f32_e32 v2, v1
	v_add_u32_e32 v74, v167, v169
	v_add_u32_e32 v204, v167, v168
	v_pk_mul_f32 v[16:17], v[60:61], v[2:3] op_sel_hi:[1,0]
	v_pk_mul_f32 v[14:15], v[58:59], v[2:3] op_sel_hi:[1,0]
	v_pk_mul_f32 v[12:13], v[64:65], v[2:3] op_sel_hi:[1,0]
	v_pk_mul_f32 v[10:11], v[62:63], v[2:3] op_sel_hi:[1,0]
	v_pk_mul_f32 v[8:9], v[68:69], v[2:3] op_sel_hi:[1,0]
	v_pk_mul_f32 v[6:7], v[66:67], v[2:3] op_sel_hi:[1,0]
	v_pk_mul_f32 v[4:5], v[72:73], v[2:3] op_sel_hi:[1,0]
	v_pk_mul_f32 v[2:3], v[70:71], v[2:3] op_sel_hi:[1,0]
	ds_read_u16 v58, v233 offset:34816
	ds_read_u16 v59, v233 offset:35088
	ds_read_u16 v60, v233 offset:35360
	ds_read_u16 v61, v233 offset:35632
	ds_read_u16 v62, v233 offset:35904
	ds_read_u16 v63, v233 offset:36176
	ds_read_u16 v64, v233 offset:36448
	ds_read_u16 v65, v233 offset:36720
	ds_read_b128 v[240:243], v204
	ds_read_b128 v[244:247], v204 offset:4352
	ds_read_b128 v[248:251], v204 offset:8704
	ds_read_b128 v[148:151], v74
	s_waitcnt lgkmcnt(4)
; #define LAS __attribute__((address_space(3)))
; __device__ __forceinline__ void ssd_phase(const bf16_t* XBC, const float* DT  , const ss_t* SSq, const float* dtb, const bf16_t* Z, const float* a_log, const float* d_skip, bf16_t* YS, LAS unsigned char* lds, int tid, int wid, int lane, int bid, int G) {
;     ...
; #pragma unroll
;                 for (int u = 0; u < 4; ++u) { unsigned short bs[8];
; #pragma unroll
;                     for (int e = 0; e < 8; ++e) bs[e] = Bt[(32 * u + 8 * fq + e) * SS_RS + 16 * wid + fr];
;                     u32x4 bq; bq.x = (unsigned)bs[0] | ((unsigned)bs[1] << 16); bq.y = (unsigned)bs[2] | ((unsigned)bs[3] << 16); bq.z = (unsigned)bs[4] | ((unsigned)bs[5] << 16); bq.w = (unsigned)bs[6] | ((unsigned)bs[7] << 16);
;                     const bf16x8 pfr = __builtin_bit_cast(bf16x8, bq);
; #pragma unroll
;                     for (int pt = 0; pt < 4; ++pt) { const bf16x8 qfr = *(const LAS bf16x8*)(XW + (16 * pt + fr) * SS_RS + 32 * u + 8 * fq); Sacc[pt] = __builtin_amdgcn_mfma_f32_16x16x32_bf16(pfr, qfr, Sacc[pt], 0, 0, 0); }
;                     __builtin_amdgcn_sched_barrier(0); }
;             }
	v_perm_b32 v70, v59, v58, s30
	v_perm_b32 v71, v61, v60, s30
	v_perm_b32 v72, v63, v62, s30
	v_perm_b32 v73, v65, v64, s30
	s_nop 1
	s_waitcnt lgkmcnt(3)
	v_mfma_f32_16x16x32_bf16 v[14:17], v[70:73], v[240:243], v[14:17]
	s_waitcnt lgkmcnt(2)
	v_mfma_f32_16x16x32_bf16 v[10:13], v[70:73], v[244:247], v[10:13]
	s_waitcnt lgkmcnt(1)
	v_mfma_f32_16x16x32_bf16 v[6:9], v[70:73], v[248:251], v[6:9]
	s_waitcnt lgkmcnt(0)
	v_mfma_f32_16x16x32_bf16 v[2:5], v[70:73], v[148:151], v[2:5]
	ds_read_u16 v58, v233 offset:43520
	ds_read_u16 v59, v233 offset:43792
	ds_read_u16 v60, v233 offset:44064
	ds_read_u16 v61, v233 offset:44336
	ds_read_u16 v62, v233 offset:44608
	ds_read_u16 v63, v233 offset:44880
	ds_read_u16 v64, v233 offset:45152
	ds_read_u16 v65, v233 offset:45424
	ds_read_b128 v[240:243], v204 offset:64
	ds_read_b128 v[244:247], v204 offset:4416
	ds_read_b128 v[248:251], v204 offset:8768
	ds_read_b128 v[148:151], v74 offset:64
	s_waitcnt lgkmcnt(4)
	v_perm_b32 v70, v59, v58, s30
	v_perm_b32 v71, v61, v60, s30
	v_perm_b32 v72, v63, v62, s30
	v_perm_b32 v73, v65, v64, s30
	s_nop 1
	s_waitcnt lgkmcnt(3)
	v_mfma_f32_16x16x32_bf16 v[14:17], v[70:73], v[240:243], v[14:17]
	s_waitcnt lgkmcnt(2)
	v_mfma_f32_16x16x32_bf16 v[10:13], v[70:73], v[244:247], v[10:13]
	s_waitcnt lgkmcnt(1)
	v_mfma_f32_16x16x32_bf16 v[6:9], v[70:73], v[248:251], v[6:9]
	s_waitcnt lgkmcnt(0)
	v_mfma_f32_16x16x32_bf16 v[2:5], v[70:73], v[148:151], v[2:5]
	ds_read_u16 v58, v233 offset:52224
	ds_read_u16 v59, v233 offset:52496
	ds_read_u16 v60, v233 offset:52768
	ds_read_u16 v61, v233 offset:53040
	ds_read_u16 v62, v233 offset:53312
	ds_read_u16 v63, v233 offset:53584
	ds_read_u16 v64, v233 offset:53856
	ds_read_u16 v65, v233 offset:54128
	ds_read_b128 v[240:243], v204 offset:128
	ds_read_b128 v[244:247], v204 offset:4480
	ds_read_b128 v[248:251], v204 offset:8832
	ds_read_b128 v[148:151], v74 offset:128
	s_waitcnt lgkmcnt(4)
	v_perm_b32 v70, v59, v58, s30
	v_perm_b32 v71, v61, v60, s30
	v_perm_b32 v72, v63, v62, s30
	v_perm_b32 v73, v65, v64, s30
	s_nop 1
	s_waitcnt lgkmcnt(3)
	v_mfma_f32_16x16x32_bf16 v[14:17], v[70:73], v[240:243], v[14:17]
	s_waitcnt lgkmcnt(2)
	v_mfma_f32_16x16x32_bf16 v[10:13], v[70:73], v[244:247], v[10:13]
	s_waitcnt lgkmcnt(1)
	v_mfma_f32_16x16x32_bf16 v[6:9], v[70:73], v[248:251], v[6:9]
	s_waitcnt lgkmcnt(0)
	v_mfma_f32_16x16x32_bf16 v[2:5], v[70:73], v[148:151], v[2:5]
	ds_read_u16 v58, v233 offset:60928
	ds_read_u16 v59, v233 offset:61200
	ds_read_u16 v60, v233 offset:61472
	ds_read_u16 v61, v233 offset:61744
	ds_read_u16 v62, v233 offset:62016
	ds_read_u16 v63, v233 offset:62288
	ds_read_u16 v64, v233 offset:62560
	ds_read_u16 v65, v233 offset:62832
	ds_read_b128 v[240:243], v204 offset:192
	ds_read_b128 v[244:247], v204 offset:4544
	ds_read_b128 v[248:251], v204 offset:8896
	ds_read_b128 v[148:151], v74 offset:192
	s_waitcnt lgkmcnt(4)
	v_perm_b32 v70, v59, v58, s30
	v_perm_b32 v71, v61, v60, s30
	v_perm_b32 v72, v63, v62, s30
	v_perm_b32 v73, v65, v64, s30
	s_nop 1
	s_waitcnt lgkmcnt(3)
	v_mfma_f32_16x16x32_bf16 v[58:61], v[70:73], v[240:243], v[14:17]
	s_waitcnt lgkmcnt(2)
	v_mfma_f32_16x16x32_bf16 v[62:65], v[70:73], v[244:247], v[10:13]
	s_waitcnt lgkmcnt(1)
	v_mfma_f32_16x16x32_bf16 v[66:69], v[70:73], v[248:251], v[6:9]
	s_waitcnt lgkmcnt(0)
	v_mfma_f32_16x16x32_bf16 v[70:73], v[70:73], v[148:151], v[2:5]
	s_mov_b64 s[30:31], 0x180000
	v_lshl_add_u64 v[134:135], v[134:135], 0, s[30:31]
	v_lshl_add_u64 v[136:137], v[136:137], 0, s[30:31]
	v_lshl_add_u64 v[140:141], v[140:141], 0, s[30:31]
	s_mov_b64 s[30:31], 0x400
	s_addk_i32 s35, 0x100
	s_mov_b64 s[36:37], 0x8000
	v_lshl_add_u64 v[158:159], v[158:159], 0, s[30:31]
	s_add_i32 s34, s34, 1
	s_mov_b64 s[30:31], 0x100000
	v_lshl_add_u64 v[138:139], v[138:139], 0, s[36:37]
	s_cmpk_eq_i32 s35, 0x1100
	v_lshl_add_u64 v[160:161], v[160:161], 0, s[30:31]
	s_cbranch_scc1 .LBB0_93
